# attention: fragment ring carried across iterations (ring of 12, mid-iteration barrier after DMA landing, bare barrier at the top)
# speedup vs baseline: 1.0063x; 1.0063x over previous
.Lfa_body:
	v_add_u32_e32 v0, s20, v156
	v_add_u32_e32 v2, v0, v148
	v_add_u32_e32 v3, v0, v150
	v_add_u32_e32 v4, v0, v152
	v_add_u32_e32 v5, v0, v154
	v_add_u32_e32 v0, s20, v157
	v_add_u32_e32 v0, 0x10000, v0
	v_add_u32_e32 v6, v0, v149
	v_add_u32_e32 v7, v0, v151
	v_add_u32_e32 v8, v0, v153
	v_add_u32_e32 v9, v0, v155
	v_subrev_u32_e32 v10, s86, v144
	v_subrev_u32_e32 v11, s76, v146
	s_waitcnt vmcnt(0) lgkmcnt(0)
	s_barrier
	ds_read_b128 v[160:163], v2 offset:32768
	ds_read_b128 v[164:167], v2 offset:40960
	ds_read_b128 v[168:171], v3 offset:32768
	ds_read_b128 v[224:227], v3 offset:40960
	ds_read_b128 v[228:231], v4 offset:32768
	ds_read_b128 v[232:235], v4 offset:40960
	ds_read_b128 v[236:239], v5 offset:32768
	ds_read_b128 v[244:247], v5 offset:40960
	ds_read_b128 v[248:251], v2 offset:49152
	ds_read_b128 v[252:255], v2 offset:57344
	ds_read_b128 v[148:151], v3 offset:49152
	ds_read_b128 v[152:155], v3 offset:57344
.Lfa_top_1:
	s_barrier
	s_mov_b32 s80, 0
	s_waitcnt lgkmcnt(10)
	v_mfma_f32_32x32x16_bf16 v[96:111], v[160:163], v[128:131], v[80:95]
	ds_read_b128 v[160:163], v4 offset:49152
	s_sub_i32 s16, s8, 64
	s_mov_b32 s17, 0
	s_lshl_b64 s[16:17], s[16:17], 11
	s_add_u32 s16, s16, s86
	s_addc_u32 s17, s17, s87
	s_add_u32 s18, s76, s6
	s_addc_u32 s19, s77, s7
	s_add_u32 s18, s18, 0x6d08000
	s_addc_u32 s19, s19, 0
	s_add_i32 m0, s24, 0x0
	s_nop 0
	global_load_lds_dwordx4 v10, s[16:17]
	v_mfma_f32_32x32x16_bf16 v[112:127], v[164:167], v[128:131], v[80:95]
	ds_read_b128 v[164:167], v4 offset:57344
	s_add_i32 m0, s24, 0x2000
	s_add_u32 s16, s16, 0x10000
	s_addc_u32 s17, s17, 0
	global_load_lds_dwordx4 v10, s[16:17]
	s_waitcnt lgkmcnt(10)
	v_mfma_f32_32x32x16_bf16 v[96:111], v[168:171], v[132:135], v[96:111]
	ds_read_b128 v[168:171], v5 offset:49152
	s_add_i32 m0, s24, 0x10000
	s_nop 0
	global_load_lds_dwordx4 v11, s[18:19]
	v_mfma_f32_32x32x16_bf16 v[112:127], v[224:227], v[132:135], v[112:127]
	ds_read_b128 v[224:227], v5 offset:57344
	s_add_i32 m0, s24, 0x12000
	s_add_u32 s18, s18, 0x2000
	s_addc_u32 s19, s19, 0
	global_load_lds_dwordx4 v11, s[18:19]
	s_waitcnt lgkmcnt(10)
	v_mfma_f32_32x32x16_bf16 v[96:111], v[228:231], v[136:139], v[96:111]
	ds_read_b128 v[228:231], v6 offset:32768
	s_add_i32 m0, s24, 0x4000
	s_add_u32 s16, s16, 0x10000
	s_addc_u32 s17, s17, 0
	global_load_lds_dwordx4 v10, s[16:17]
	v_mfma_f32_32x32x16_bf16 v[112:127], v[232:235], v[136:139], v[112:127]
	ds_read_b128 v[232:235], v6 offset:36864
	s_add_i32 m0, s24, 0x6000
	s_add_u32 s16, s16, 0x10000
	s_addc_u32 s17, s17, 0
	global_load_lds_dwordx4 v10, s[16:17]
	s_waitcnt lgkmcnt(10)
	v_mfma_f32_32x32x16_bf16 v[96:111], v[236:239], v[140:143], v[96:111]
	ds_read_b128 v[236:239], v6 offset:40960
	s_add_i32 m0, s24, 0x14000
	s_add_u32 s18, s18, 0x2000
	s_addc_u32 s19, s19, 0
	global_load_lds_dwordx4 v11, s[18:19]
	v_mfma_f32_32x32x16_bf16 v[112:127], v[244:247], v[140:143], v[112:127]
	ds_read_b128 v[244:247], v6 offset:45056
	s_add_i32 m0, s24, 0x16000
	s_add_u32 s18, s18, 0x2000
	s_addc_u32 s19, s19, 0
	global_load_lds_dwordx4 v11, s[18:19]
	s_waitcnt lgkmcnt(10)
	v_mfma_f32_32x32x16_bf16 v[192:207], v[248:251], v[128:131], v[80:95]
	ds_read_b128 v[248:251], v7 offset:32768
	s_mov_b64 s[18:19], 0
	v_max3_f32 v190, v96, v97, v98
	v_max3_f32 v190, v190, v99, v100
	v_max3_f32 v190, v190, v101, v102
	v_max3_f32 v190, v190, v103, v104
	v_mfma_f32_32x32x16_bf16 v[208:223], v[252:255], v[128:131], v[80:95]
	ds_read_b128 v[252:255], v7 offset:36864
	v_max3_f32 v190, v190, v105, v106
	v_max3_f32 v190, v190, v107, v108
	v_max3_f32 v190, v190, v109, v110
	v_max3_f32 v190, v190, v111, v111
	v_max3_f32 v191, v112, v113, v114
	v_max3_f32 v191, v191, v115, v116
	s_waitcnt lgkmcnt(10)
	v_mfma_f32_32x32x16_bf16 v[192:207], v[148:151], v[132:135], v[192:207]
	ds_read_b128 v[148:151], v7 offset:40960
	v_max3_f32 v191, v191, v117, v118
	v_max3_f32 v191, v191, v119, v120
	v_max3_f32 v191, v191, v121, v122
	v_max3_f32 v191, v191, v123, v124
	v_max3_f32 v191, v191, v125, v126
	v_max3_f32 v191, v191, v127, v127
	v_mfma_f32_32x32x16_bf16 v[208:223], v[152:155], v[132:135], v[208:223]
	ds_read_b128 v[152:155], v7 offset:45056
	v_max_f32_e32 v0, v190, v191
	s_nop 0
	v_cmp_lt_f32_e32 vcc, s67, v0
	s_cbranch_vccnz .Lfa_rareA_1
.Lfa_retA_1:
	s_waitcnt lgkmcnt(10)
	v_mfma_f32_32x32x16_bf16 v[192:207], v[160:163], v[136:139], v[192:207]
	ds_read_b128 v[160:163], v8 offset:32768
	v_exp_f32_e32 v96, v96
	v_exp_f32_e32 v97, v97
	v_exp_f32_e32 v98, v98
	v_exp_f32_e32 v99, v99
	v_exp_f32_e32 v100, v100
	v_mfma_f32_32x32x16_bf16 v[208:223], v[164:167], v[136:139], v[208:223]
	ds_read_b128 v[164:167], v8 offset:36864
	v_exp_f32_e32 v101, v101
	v_exp_f32_e32 v102, v102
	v_exp_f32_e32 v103, v103
	v_add_f32_e32 v159, v159, v96
	v_add_f32_e32 v159, v159, v97
	s_waitcnt lgkmcnt(10)
	v_mfma_f32_32x32x16_bf16 v[192:207], v[168:171], v[140:143], v[192:207]
	ds_read_b128 v[168:171], v8 offset:40960
	v_add_f32_e32 v159, v159, v98
	v_add_f32_e32 v159, v159, v99
	v_cvt_pk_bf16_f32 v96, v96, v97
	v_cvt_pk_bf16_f32 v97, v98, v99
	v_add_f32_e32 v159, v159, v100
	v_mfma_f32_32x32x16_bf16 v[208:223], v[224:227], v[140:143], v[208:223]
	ds_read_b128 v[224:227], v8 offset:45056
	v_add_f32_e32 v159, v159, v101
	v_cvt_pk_bf16_f32 v98, v100, v101
	v_cvt_pk_bf16_f32 v99, v102, v103
	v_add_f32_e32 v159, v159, v102
	v_add_f32_e32 v159, v159, v103
	s_waitcnt lgkmcnt(10)
	v_mfma_f32_32x32x16_bf16 v[64:79], v[228:231], v[96:99], v[64:79]
	ds_read_b128 v[228:231], v9 offset:32768
	v_exp_f32_e32 v104, v104
	v_exp_f32_e32 v105, v105
	v_exp_f32_e32 v106, v106
	v_exp_f32_e32 v107, v107
	v_exp_f32_e32 v108, v108
	v_mfma_f32_32x32x16_bf16 v[48:63], v[232:235], v[96:99], v[48:63]
	ds_read_b128 v[232:235], v9 offset:36864
	v_exp_f32_e32 v109, v109
	v_exp_f32_e32 v110, v110
	v_exp_f32_e32 v111, v111
	v_add_f32_e32 v159, v159, v104
	v_add_f32_e32 v159, v159, v105
	s_waitcnt lgkmcnt(10)
	v_mfma_f32_32x32x16_bf16 v[32:47], v[236:239], v[96:99], v[32:47]
	ds_read_b128 v[236:239], v9 offset:40960
	v_add_f32_e32 v159, v159, v106
	v_add_f32_e32 v159, v159, v107
	v_cvt_pk_bf16_f32 v104, v104, v105
	v_cvt_pk_bf16_f32 v105, v106, v107
	v_add_f32_e32 v159, v159, v108
	v_mfma_f32_32x32x16_bf16 v[16:31], v[244:247], v[96:99], v[16:31]
	ds_read_b128 v[244:247], v9 offset:45056
	v_add_f32_e32 v159, v159, v109
	v_cvt_pk_bf16_f32 v106, v108, v109
	v_cvt_pk_bf16_f32 v107, v110, v111
	v_add_f32_e32 v159, v159, v110
	v_add_f32_e32 v159, v159, v111
	s_waitcnt lgkmcnt(10)
	v_mfma_f32_32x32x16_bf16 v[64:79], v[248:251], v[104:107], v[64:79]
	ds_read_b128 v[248:251], v6 offset:49152
	v_exp_f32_e32 v112, v112
	v_exp_f32_e32 v113, v113
	v_exp_f32_e32 v114, v114
	v_exp_f32_e32 v115, v115
	v_exp_f32_e32 v116, v116
	v_mfma_f32_32x32x16_bf16 v[48:63], v[252:255], v[104:107], v[48:63]
	ds_read_b128 v[252:255], v6 offset:53248
	v_exp_f32_e32 v117, v117
	v_exp_f32_e32 v118, v118
	v_exp_f32_e32 v119, v119
	v_add_f32_e32 v159, v159, v112
	v_add_f32_e32 v159, v159, v113
	s_waitcnt lgkmcnt(10)
	v_mfma_f32_32x32x16_bf16 v[32:47], v[148:151], v[104:107], v[32:47]
	ds_read_b128 v[148:151], v6 offset:57344
	v_add_f32_e32 v159, v159, v114
	v_add_f32_e32 v159, v159, v115
	v_cvt_pk_bf16_f32 v112, v112, v113
	v_cvt_pk_bf16_f32 v113, v114, v115
	v_add_f32_e32 v159, v159, v116
	v_mfma_f32_32x32x16_bf16 v[16:31], v[152:155], v[104:107], v[16:31]
	ds_read_b128 v[152:155], v6 offset:61440
	v_add_f32_e32 v159, v159, v117
	v_cvt_pk_bf16_f32 v114, v116, v117
	v_cvt_pk_bf16_f32 v115, v118, v119
	v_add_f32_e32 v159, v159, v118
	v_add_f32_e32 v159, v159, v119
	s_waitcnt lgkmcnt(10)
	v_mfma_f32_32x32x16_bf16 v[64:79], v[160:163], v[112:115], v[64:79]
	ds_read_b128 v[160:163], v7 offset:49152
	v_exp_f32_e32 v120, v120
	v_exp_f32_e32 v121, v121
	v_exp_f32_e32 v122, v122
	v_exp_f32_e32 v123, v123
	v_exp_f32_e32 v124, v124
	v_max3_f32 v190, v192, v193, v194
	v_max3_f32 v190, v190, v195, v196
	v_max3_f32 v190, v190, v197, v198
	v_max3_f32 v190, v190, v199, v200
	v_mfma_f32_32x32x16_bf16 v[48:63], v[164:167], v[112:115], v[48:63]
	ds_read_b128 v[164:167], v7 offset:53248
	v_exp_f32_e32 v125, v125
	v_exp_f32_e32 v126, v126
	v_exp_f32_e32 v127, v127
	v_add_f32_e32 v159, v159, v120
	v_add_f32_e32 v159, v159, v121
	v_max3_f32 v190, v190, v201, v202
	v_max3_f32 v190, v190, v203, v204
	v_max3_f32 v190, v190, v205, v206
	v_max3_f32 v190, v190, v207, v207
	s_waitcnt lgkmcnt(10)
	v_mfma_f32_32x32x16_bf16 v[32:47], v[168:171], v[112:115], v[32:47]
	ds_read_b128 v[168:171], v7 offset:57344
	v_add_f32_e32 v159, v159, v122
	v_add_f32_e32 v159, v159, v123
	v_cvt_pk_bf16_f32 v120, v120, v121
	v_cvt_pk_bf16_f32 v121, v122, v123
	v_add_f32_e32 v159, v159, v124
	v_max3_f32 v191, v208, v209, v210
	v_max3_f32 v191, v191, v211, v212
	v_max3_f32 v191, v191, v213, v214
	v_max3_f32 v191, v191, v215, v216
	v_mfma_f32_32x32x16_bf16 v[16:31], v[224:227], v[112:115], v[16:31]
	ds_read_b128 v[224:227], v7 offset:61440
	v_add_f32_e32 v159, v159, v125
	v_cvt_pk_bf16_f32 v122, v124, v125
	v_cvt_pk_bf16_f32 v123, v126, v127
	v_add_f32_e32 v159, v159, v126
	v_add_f32_e32 v159, v159, v127
	v_max3_f32 v191, v191, v217, v218
	v_max3_f32 v191, v191, v219, v220
	v_max3_f32 v191, v191, v221, v222
	v_max3_f32 v191, v191, v223, v223
	s_waitcnt lgkmcnt(10)
	v_mfma_f32_32x32x16_bf16 v[64:79], v[228:231], v[120:123], v[64:79]
	ds_read_b128 v[228:231], v8 offset:49152
	v_max_f32_e32 v0, v190, v191
	s_nop 0
	v_cmp_lt_f32_e32 vcc, s67, v0
	s_or_b64 vcc, vcc, s[18:19]
	s_cbranch_vccnz .Lfa_rareB_1
.Lfa_retB_1:
	v_exp_f32_e32 v192, v192
	v_exp_f32_e32 v193, v193
	v_exp_f32_e32 v194, v194
	v_exp_f32_e32 v195, v195
	v_exp_f32_e32 v196, v196
	v_mfma_f32_32x32x16_bf16 v[48:63], v[232:235], v[120:123], v[48:63]
	ds_read_b128 v[232:235], v8 offset:53248
	v_exp_f32_e32 v197, v197
	v_exp_f32_e32 v198, v198
	v_exp_f32_e32 v199, v199
	v_add_f32_e32 v159, v159, v192
	v_add_f32_e32 v159, v159, v193
	s_waitcnt lgkmcnt(10)
	v_mfma_f32_32x32x16_bf16 v[32:47], v[236:239], v[120:123], v[32:47]
	ds_read_b128 v[236:239], v8 offset:57344
	v_add_f32_e32 v159, v159, v194
	v_add_f32_e32 v159, v159, v195
	v_cvt_pk_bf16_f32 v192, v192, v193
	v_cvt_pk_bf16_f32 v193, v194, v195
	v_add_f32_e32 v159, v159, v196
	v_mfma_f32_32x32x16_bf16 v[16:31], v[244:247], v[120:123], v[16:31]
	ds_read_b128 v[244:247], v8 offset:61440
	v_add_f32_e32 v159, v159, v197
	v_cvt_pk_bf16_f32 v194, v196, v197
	v_cvt_pk_bf16_f32 v195, v198, v199
	v_add_f32_e32 v159, v159, v198
	v_add_f32_e32 v159, v159, v199
	s_cmp_lg_u32 s80, 0
	s_cbranch_scc1 .Lfa_fixO_1
.Lfa_retO_1:
	s_waitcnt lgkmcnt(10)
	v_mfma_f32_32x32x16_bf16 v[64:79], v[248:251], v[192:195], v[64:79]
	ds_read_b128 v[248:251], v9 offset:49152
	v_exp_f32_e32 v200, v200
	v_exp_f32_e32 v201, v201
	v_exp_f32_e32 v202, v202
	v_exp_f32_e32 v203, v203
	v_exp_f32_e32 v204, v204
	v_mfma_f32_32x32x16_bf16 v[48:63], v[252:255], v[192:195], v[48:63]
	ds_read_b128 v[252:255], v9 offset:53248
	v_exp_f32_e32 v205, v205
	v_exp_f32_e32 v206, v206
	v_exp_f32_e32 v207, v207
	v_add_f32_e32 v159, v159, v200
	v_add_f32_e32 v159, v159, v201
	s_waitcnt lgkmcnt(10)
	v_mfma_f32_32x32x16_bf16 v[32:47], v[148:151], v[192:195], v[32:47]
	ds_read_b128 v[148:151], v9 offset:57344
	v_add_f32_e32 v159, v159, v202
	v_add_f32_e32 v159, v159, v203
	v_cvt_pk_bf16_f32 v200, v200, v201
	v_cvt_pk_bf16_f32 v201, v202, v203
	v_add_f32_e32 v159, v159, v204
	v_mfma_f32_32x32x16_bf16 v[16:31], v[152:155], v[192:195], v[16:31]
	ds_read_b128 v[152:155], v9 offset:61440
	v_add_f32_e32 v159, v159, v205
	v_cvt_pk_bf16_f32 v202, v204, v205
	v_cvt_pk_bf16_f32 v203, v206, v207
	v_add_f32_e32 v159, v159, v206
	v_add_f32_e32 v159, v159, v207
	s_waitcnt vmcnt(0)
	s_barrier
	s_waitcnt lgkmcnt(10)
	v_mfma_f32_32x32x16_bf16 v[64:79], v[160:163], v[200:203], v[64:79]
	ds_read_b128 v[160:163], v2
	v_exp_f32_e32 v208, v208
	v_exp_f32_e32 v209, v209
	v_exp_f32_e32 v210, v210
	v_exp_f32_e32 v211, v211
	v_exp_f32_e32 v212, v212
	v_mfma_f32_32x32x16_bf16 v[48:63], v[164:167], v[200:203], v[48:63]
	ds_read_b128 v[164:167], v2 offset:8192
	v_exp_f32_e32 v213, v213
	v_exp_f32_e32 v214, v214
	v_exp_f32_e32 v215, v215
	v_add_f32_e32 v159, v159, v208
	v_add_f32_e32 v159, v159, v209
	s_waitcnt lgkmcnt(10)
	v_mfma_f32_32x32x16_bf16 v[32:47], v[168:171], v[200:203], v[32:47]
	ds_read_b128 v[168:171], v3
	v_add_f32_e32 v159, v159, v210
	v_add_f32_e32 v159, v159, v211
	v_cvt_pk_bf16_f32 v208, v208, v209
	v_cvt_pk_bf16_f32 v209, v210, v211
	v_add_f32_e32 v159, v159, v212
	v_mfma_f32_32x32x16_bf16 v[16:31], v[224:227], v[200:203], v[16:31]
	ds_read_b128 v[224:227], v3 offset:8192
	v_add_f32_e32 v159, v159, v213
	v_cvt_pk_bf16_f32 v210, v212, v213
	v_cvt_pk_bf16_f32 v211, v214, v215
	v_add_f32_e32 v159, v159, v214
	v_add_f32_e32 v159, v159, v215
	s_waitcnt lgkmcnt(10)
	v_mfma_f32_32x32x16_bf16 v[64:79], v[228:231], v[208:211], v[64:79]
	ds_read_b128 v[228:231], v4
	v_exp_f32_e32 v216, v216
	v_exp_f32_e32 v217, v217
	v_exp_f32_e32 v218, v218
	v_exp_f32_e32 v219, v219
	v_exp_f32_e32 v220, v220
	v_mfma_f32_32x32x16_bf16 v[48:63], v[232:235], v[208:211], v[48:63]
	ds_read_b128 v[232:235], v4 offset:8192
	v_exp_f32_e32 v221, v221
	v_exp_f32_e32 v222, v222
	v_exp_f32_e32 v223, v223
	v_add_f32_e32 v159, v159, v216
	v_add_f32_e32 v159, v159, v217
	s_waitcnt lgkmcnt(10)
	v_mfma_f32_32x32x16_bf16 v[32:47], v[236:239], v[208:211], v[32:47]
	ds_read_b128 v[236:239], v5
	v_add_f32_e32 v159, v159, v218
	v_add_f32_e32 v159, v159, v219
	v_cvt_pk_bf16_f32 v216, v216, v217
	v_cvt_pk_bf16_f32 v217, v218, v219
	v_add_f32_e32 v159, v159, v220
	v_mfma_f32_32x32x16_bf16 v[16:31], v[244:247], v[208:211], v[16:31]
	ds_read_b128 v[244:247], v5 offset:8192
	v_add_f32_e32 v159, v159, v221
	v_cvt_pk_bf16_f32 v218, v220, v221
	v_cvt_pk_bf16_f32 v219, v222, v223
	v_add_f32_e32 v159, v159, v222
	v_add_f32_e32 v159, v159, v223
	s_waitcnt lgkmcnt(10)
	v_mfma_f32_32x32x16_bf16 v[64:79], v[248:251], v[216:219], v[64:79]
	ds_read_b128 v[248:251], v2 offset:16384
	s_add_i32 s26, s26, 1
	s_add_u32 s6, s6, 0x8000
	v_mfma_f32_32x32x16_bf16 v[48:63], v[252:255], v[216:219], v[48:63]
	ds_read_b128 v[252:255], v2 offset:24576
	s_addc_u32 s7, s7, 0
	s_addk_i32 s8, 0x80
	s_waitcnt lgkmcnt(10)
	v_mfma_f32_32x32x16_bf16 v[32:47], v[148:151], v[216:219], v[32:47]
	ds_read_b128 v[148:151], v3 offset:16384
	v_add_u32_e32 v158, 0xffffff80, v158
	v_mfma_f32_32x32x16_bf16 v[16:31], v[152:155], v[216:219], v[16:31]
	ds_read_b128 v[152:155], v3 offset:24576
	s_cmp_lt_i32 s26, s5
	s_cbranch_scc0 .Lfa_exit
.Lfa_top_0:
	s_barrier
	s_mov_b32 s80, 0
	s_waitcnt lgkmcnt(10)
	v_mfma_f32_32x32x16_bf16 v[96:111], v[160:163], v[128:131], v[80:95]
	ds_read_b128 v[160:163], v4 offset:16384
	s_sub_i32 s16, s8, 64
	s_mov_b32 s17, 0
	s_lshl_b64 s[16:17], s[16:17], 11
	s_add_u32 s16, s16, s86
	s_addc_u32 s17, s17, s87
	s_add_u32 s18, s76, s6
	s_addc_u32 s19, s77, s7
	s_add_u32 s18, s18, 0x6d08000
	s_addc_u32 s19, s19, 0
	s_add_i32 m0, s24, 0x8000
	s_nop 0
	global_load_lds_dwordx4 v10, s[16:17]
	v_mfma_f32_32x32x16_bf16 v[112:127], v[164:167], v[128:131], v[80:95]
	ds_read_b128 v[164:167], v4 offset:24576
	s_add_i32 m0, s24, 0xa000
	s_add_u32 s16, s16, 0x10000
	s_addc_u32 s17, s17, 0
	global_load_lds_dwordx4 v10, s[16:17]
	s_waitcnt lgkmcnt(10)
	v_mfma_f32_32x32x16_bf16 v[96:111], v[168:171], v[132:135], v[96:111]
	ds_read_b128 v[168:171], v5 offset:16384
	s_add_i32 m0, s24, 0x18000
	s_nop 0
	global_load_lds_dwordx4 v11, s[18:19]
	v_mfma_f32_32x32x16_bf16 v[112:127], v[224:227], v[132:135], v[112:127]
	ds_read_b128 v[224:227], v5 offset:24576
	s_add_i32 m0, s24, 0x1a000
	s_add_u32 s18, s18, 0x2000
	s_addc_u32 s19, s19, 0
	global_load_lds_dwordx4 v11, s[18:19]
	s_waitcnt lgkmcnt(10)
	v_mfma_f32_32x32x16_bf16 v[96:111], v[228:231], v[136:139], v[96:111]
	ds_read_b128 v[228:231], v6
	s_add_i32 m0, s24, 0xc000
	s_add_u32 s16, s16, 0x10000
	s_addc_u32 s17, s17, 0
	global_load_lds_dwordx4 v10, s[16:17]
	v_mfma_f32_32x32x16_bf16 v[112:127], v[232:235], v[136:139], v[112:127]
	ds_read_b128 v[232:235], v6 offset:4096
	s_add_i32 m0, s24, 0xe000
	s_add_u32 s16, s16, 0x10000
	s_addc_u32 s17, s17, 0
	global_load_lds_dwordx4 v10, s[16:17]
	s_waitcnt lgkmcnt(10)
	v_mfma_f32_32x32x16_bf16 v[96:111], v[236:239], v[140:143], v[96:111]
	ds_read_b128 v[236:239], v6 offset:8192
	s_add_i32 m0, s24, 0x1c000
	s_add_u32 s18, s18, 0x2000
	s_addc_u32 s19, s19, 0
	global_load_lds_dwordx4 v11, s[18:19]
	v_mfma_f32_32x32x16_bf16 v[112:127], v[244:247], v[140:143], v[112:127]
	ds_read_b128 v[244:247], v6 offset:12288
	s_add_i32 m0, s24, 0x1e000
	s_add_u32 s18, s18, 0x2000
	s_addc_u32 s19, s19, 0
	global_load_lds_dwordx4 v11, s[18:19]
	s_waitcnt lgkmcnt(10)
	v_mfma_f32_32x32x16_bf16 v[192:207], v[248:251], v[128:131], v[80:95]
	ds_read_b128 v[248:251], v7
	s_mov_b64 s[18:19], 0
	v_max3_f32 v190, v96, v97, v98
	v_max3_f32 v190, v190, v99, v100
	v_max3_f32 v190, v190, v101, v102
	v_max3_f32 v190, v190, v103, v104
	v_mfma_f32_32x32x16_bf16 v[208:223], v[252:255], v[128:131], v[80:95]
	ds_read_b128 v[252:255], v7 offset:4096
	v_max3_f32 v190, v190, v105, v106
	v_max3_f32 v190, v190, v107, v108
	v_max3_f32 v190, v190, v109, v110
	v_max3_f32 v190, v190, v111, v111
	v_max3_f32 v191, v112, v113, v114
	v_max3_f32 v191, v191, v115, v116
	s_waitcnt lgkmcnt(10)
	v_mfma_f32_32x32x16_bf16 v[192:207], v[148:151], v[132:135], v[192:207]
	ds_read_b128 v[148:151], v7 offset:8192
	v_max3_f32 v191, v191, v117, v118
	v_max3_f32 v191, v191, v119, v120
	v_max3_f32 v191, v191, v121, v122
	v_max3_f32 v191, v191, v123, v124
	v_max3_f32 v191, v191, v125, v126
	v_max3_f32 v191, v191, v127, v127
	v_mfma_f32_32x32x16_bf16 v[208:223], v[152:155], v[132:135], v[208:223]
	ds_read_b128 v[152:155], v7 offset:12288
	v_max_f32_e32 v0, v190, v191
	s_nop 0
	v_cmp_lt_f32_e32 vcc, s67, v0
	s_cbranch_vccnz .Lfa_rareA_0
.Lfa_retA_0:
	s_waitcnt lgkmcnt(10)
	v_mfma_f32_32x32x16_bf16 v[192:207], v[160:163], v[136:139], v[192:207]
	ds_read_b128 v[160:163], v8
	v_exp_f32_e32 v96, v96
	v_exp_f32_e32 v97, v97
	v_exp_f32_e32 v98, v98
	v_exp_f32_e32 v99, v99
	v_exp_f32_e32 v100, v100
	v_mfma_f32_32x32x16_bf16 v[208:223], v[164:167], v[136:139], v[208:223]
	ds_read_b128 v[164:167], v8 offset:4096
	v_exp_f32_e32 v101, v101
	v_exp_f32_e32 v102, v102
	v_exp_f32_e32 v103, v103
	v_add_f32_e32 v159, v159, v96
	v_add_f32_e32 v159, v159, v97
	s_waitcnt lgkmcnt(10)
	v_mfma_f32_32x32x16_bf16 v[192:207], v[168:171], v[140:143], v[192:207]
	ds_read_b128 v[168:171], v8 offset:8192
	v_add_f32_e32 v159, v159, v98
	v_add_f32_e32 v159, v159, v99
	v_cvt_pk_bf16_f32 v96, v96, v97
	v_cvt_pk_bf16_f32 v97, v98, v99
	v_add_f32_e32 v159, v159, v100
	v_mfma_f32_32x32x16_bf16 v[208:223], v[224:227], v[140:143], v[208:223]
	ds_read_b128 v[224:227], v8 offset:12288
	v_add_f32_e32 v159, v159, v101
	v_cvt_pk_bf16_f32 v98, v100, v101
	v_cvt_pk_bf16_f32 v99, v102, v103
	v_add_f32_e32 v159, v159, v102
	v_add_f32_e32 v159, v159, v103
	s_waitcnt lgkmcnt(10)
	v_mfma_f32_32x32x16_bf16 v[64:79], v[228:231], v[96:99], v[64:79]
	ds_read_b128 v[228:231], v9
	v_exp_f32_e32 v104, v104
	v_exp_f32_e32 v105, v105
	v_exp_f32_e32 v106, v106
	v_exp_f32_e32 v107, v107
	v_exp_f32_e32 v108, v108
	v_mfma_f32_32x32x16_bf16 v[48:63], v[232:235], v[96:99], v[48:63]
	ds_read_b128 v[232:235], v9 offset:4096
	v_exp_f32_e32 v109, v109
	v_exp_f32_e32 v110, v110
	v_exp_f32_e32 v111, v111
	v_add_f32_e32 v159, v159, v104
	v_add_f32_e32 v159, v159, v105
	s_waitcnt lgkmcnt(10)
	v_mfma_f32_32x32x16_bf16 v[32:47], v[236:239], v[96:99], v[32:47]
	ds_read_b128 v[236:239], v9 offset:8192
	v_add_f32_e32 v159, v159, v106
	v_add_f32_e32 v159, v159, v107
	v_cvt_pk_bf16_f32 v104, v104, v105
	v_cvt_pk_bf16_f32 v105, v106, v107
	v_add_f32_e32 v159, v159, v108
	v_mfma_f32_32x32x16_bf16 v[16:31], v[244:247], v[96:99], v[16:31]
	ds_read_b128 v[244:247], v9 offset:12288
	v_add_f32_e32 v159, v159, v109
	v_cvt_pk_bf16_f32 v106, v108, v109
	v_cvt_pk_bf16_f32 v107, v110, v111
	v_add_f32_e32 v159, v159, v110
	v_add_f32_e32 v159, v159, v111
	s_waitcnt lgkmcnt(10)
	v_mfma_f32_32x32x16_bf16 v[64:79], v[248:251], v[104:107], v[64:79]
	ds_read_b128 v[248:251], v6 offset:16384
	v_exp_f32_e32 v112, v112
	v_exp_f32_e32 v113, v113
	v_exp_f32_e32 v114, v114
	v_exp_f32_e32 v115, v115
	v_exp_f32_e32 v116, v116
	v_mfma_f32_32x32x16_bf16 v[48:63], v[252:255], v[104:107], v[48:63]
	ds_read_b128 v[252:255], v6 offset:20480
	v_exp_f32_e32 v117, v117
	v_exp_f32_e32 v118, v118
	v_exp_f32_e32 v119, v119
	v_add_f32_e32 v159, v159, v112
	v_add_f32_e32 v159, v159, v113
	s_waitcnt lgkmcnt(10)
	v_mfma_f32_32x32x16_bf16 v[32:47], v[148:151], v[104:107], v[32:47]
	ds_read_b128 v[148:151], v6 offset:24576
	v_add_f32_e32 v159, v159, v114
	v_add_f32_e32 v159, v159, v115
	v_cvt_pk_bf16_f32 v112, v112, v113
	v_cvt_pk_bf16_f32 v113, v114, v115
	v_add_f32_e32 v159, v159, v116
	v_mfma_f32_32x32x16_bf16 v[16:31], v[152:155], v[104:107], v[16:31]
	ds_read_b128 v[152:155], v6 offset:28672
	v_add_f32_e32 v159, v159, v117
	v_cvt_pk_bf16_f32 v114, v116, v117
	v_cvt_pk_bf16_f32 v115, v118, v119
	v_add_f32_e32 v159, v159, v118
	v_add_f32_e32 v159, v159, v119
	s_waitcnt lgkmcnt(10)
	v_mfma_f32_32x32x16_bf16 v[64:79], v[160:163], v[112:115], v[64:79]
	ds_read_b128 v[160:163], v7 offset:16384
	v_exp_f32_e32 v120, v120
	v_exp_f32_e32 v121, v121
	v_exp_f32_e32 v122, v122
	v_exp_f32_e32 v123, v123
	v_exp_f32_e32 v124, v124
	v_max3_f32 v190, v192, v193, v194
	v_max3_f32 v190, v190, v195, v196
	v_max3_f32 v190, v190, v197, v198
	v_max3_f32 v190, v190, v199, v200
	v_mfma_f32_32x32x16_bf16 v[48:63], v[164:167], v[112:115], v[48:63]
	ds_read_b128 v[164:167], v7 offset:20480
	v_exp_f32_e32 v125, v125
	v_exp_f32_e32 v126, v126
	v_exp_f32_e32 v127, v127
	v_add_f32_e32 v159, v159, v120
	v_add_f32_e32 v159, v159, v121
	v_max3_f32 v190, v190, v201, v202
	v_max3_f32 v190, v190, v203, v204
	v_max3_f32 v190, v190, v205, v206
	v_max3_f32 v190, v190, v207, v207
	s_waitcnt lgkmcnt(10)
	v_mfma_f32_32x32x16_bf16 v[32:47], v[168:171], v[112:115], v[32:47]
	ds_read_b128 v[168:171], v7 offset:24576
	v_add_f32_e32 v159, v159, v122
	v_add_f32_e32 v159, v159, v123
	v_cvt_pk_bf16_f32 v120, v120, v121
	v_cvt_pk_bf16_f32 v121, v122, v123
	v_add_f32_e32 v159, v159, v124
	v_max3_f32 v191, v208, v209, v210
	v_max3_f32 v191, v191, v211, v212
	v_max3_f32 v191, v191, v213, v214
	v_max3_f32 v191, v191, v215, v216
	v_mfma_f32_32x32x16_bf16 v[16:31], v[224:227], v[112:115], v[16:31]
	ds_read_b128 v[224:227], v7 offset:28672
	v_add_f32_e32 v159, v159, v125
	v_cvt_pk_bf16_f32 v122, v124, v125
	v_cvt_pk_bf16_f32 v123, v126, v127
	v_add_f32_e32 v159, v159, v126
	v_add_f32_e32 v159, v159, v127
	v_max3_f32 v191, v191, v217, v218
	v_max3_f32 v191, v191, v219, v220
	v_max3_f32 v191, v191, v221, v222
	v_max3_f32 v191, v191, v223, v223
	s_waitcnt lgkmcnt(10)
	v_mfma_f32_32x32x16_bf16 v[64:79], v[228:231], v[120:123], v[64:79]
	ds_read_b128 v[228:231], v8 offset:16384
	v_max_f32_e32 v0, v190, v191
	s_nop 0
	v_cmp_lt_f32_e32 vcc, s67, v0
	s_or_b64 vcc, vcc, s[18:19]
	s_cbranch_vccnz .Lfa_rareB_0
.Lfa_retB_0:
	v_exp_f32_e32 v192, v192
	v_exp_f32_e32 v193, v193
	v_exp_f32_e32 v194, v194
	v_exp_f32_e32 v195, v195
	v_exp_f32_e32 v196, v196
	v_mfma_f32_32x32x16_bf16 v[48:63], v[232:235], v[120:123], v[48:63]
	ds_read_b128 v[232:235], v8 offset:20480
	v_exp_f32_e32 v197, v197
	v_exp_f32_e32 v198, v198
	v_exp_f32_e32 v199, v199
	v_add_f32_e32 v159, v159, v192
	v_add_f32_e32 v159, v159, v193
	s_waitcnt lgkmcnt(10)
	v_mfma_f32_32x32x16_bf16 v[32:47], v[236:239], v[120:123], v[32:47]
	ds_read_b128 v[236:239], v8 offset:24576
	v_add_f32_e32 v159, v159, v194
	v_add_f32_e32 v159, v159, v195
	v_cvt_pk_bf16_f32 v192, v192, v193
	v_cvt_pk_bf16_f32 v193, v194, v195
	v_add_f32_e32 v159, v159, v196
	v_mfma_f32_32x32x16_bf16 v[16:31], v[244:247], v[120:123], v[16:31]
	ds_read_b128 v[244:247], v8 offset:28672
	v_add_f32_e32 v159, v159, v197
	v_cvt_pk_bf16_f32 v194, v196, v197
	v_cvt_pk_bf16_f32 v195, v198, v199
	v_add_f32_e32 v159, v159, v198
	v_add_f32_e32 v159, v159, v199
	s_cmp_lg_u32 s80, 0
	s_cbranch_scc1 .Lfa_fixO_0
.Lfa_retO_0:
	s_waitcnt lgkmcnt(10)
	v_mfma_f32_32x32x16_bf16 v[64:79], v[248:251], v[192:195], v[64:79]
	ds_read_b128 v[248:251], v9 offset:16384
	v_exp_f32_e32 v200, v200
	v_exp_f32_e32 v201, v201
	v_exp_f32_e32 v202, v202
	v_exp_f32_e32 v203, v203
	v_exp_f32_e32 v204, v204
	v_mfma_f32_32x32x16_bf16 v[48:63], v[252:255], v[192:195], v[48:63]
	ds_read_b128 v[252:255], v9 offset:20480
	v_exp_f32_e32 v205, v205
	v_exp_f32_e32 v206, v206
	v_exp_f32_e32 v207, v207
	v_add_f32_e32 v159, v159, v200
	v_add_f32_e32 v159, v159, v201
	s_waitcnt lgkmcnt(10)
	v_mfma_f32_32x32x16_bf16 v[32:47], v[148:151], v[192:195], v[32:47]
	ds_read_b128 v[148:151], v9 offset:24576
	v_add_f32_e32 v159, v159, v202
	v_add_f32_e32 v159, v159, v203
	v_cvt_pk_bf16_f32 v200, v200, v201
	v_cvt_pk_bf16_f32 v201, v202, v203
	v_add_f32_e32 v159, v159, v204
	v_mfma_f32_32x32x16_bf16 v[16:31], v[152:155], v[192:195], v[16:31]
	ds_read_b128 v[152:155], v9 offset:28672
	v_add_f32_e32 v159, v159, v205
	v_cvt_pk_bf16_f32 v202, v204, v205
	v_cvt_pk_bf16_f32 v203, v206, v207
	v_add_f32_e32 v159, v159, v206
	v_add_f32_e32 v159, v159, v207
	s_waitcnt vmcnt(0)
	s_barrier
	s_waitcnt lgkmcnt(10)
	v_mfma_f32_32x32x16_bf16 v[64:79], v[160:163], v[200:203], v[64:79]
	ds_read_b128 v[160:163], v2 offset:32768
	v_exp_f32_e32 v208, v208
	v_exp_f32_e32 v209, v209
	v_exp_f32_e32 v210, v210
	v_exp_f32_e32 v211, v211
	v_exp_f32_e32 v212, v212
	v_mfma_f32_32x32x16_bf16 v[48:63], v[164:167], v[200:203], v[48:63]
	ds_read_b128 v[164:167], v2 offset:40960
	v_exp_f32_e32 v213, v213
	v_exp_f32_e32 v214, v214
	v_exp_f32_e32 v215, v215
	v_add_f32_e32 v159, v159, v208
	v_add_f32_e32 v159, v159, v209
	s_waitcnt lgkmcnt(10)
	v_mfma_f32_32x32x16_bf16 v[32:47], v[168:171], v[200:203], v[32:47]
	ds_read_b128 v[168:171], v3 offset:32768
	v_add_f32_e32 v159, v159, v210
	v_add_f32_e32 v159, v159, v211
	v_cvt_pk_bf16_f32 v208, v208, v209
	v_cvt_pk_bf16_f32 v209, v210, v211
	v_add_f32_e32 v159, v159, v212
	v_mfma_f32_32x32x16_bf16 v[16:31], v[224:227], v[200:203], v[16:31]
	ds_read_b128 v[224:227], v3 offset:40960
	v_add_f32_e32 v159, v159, v213
	v_cvt_pk_bf16_f32 v210, v212, v213
	v_cvt_pk_bf16_f32 v211, v214, v215
	v_add_f32_e32 v159, v159, v214
	v_add_f32_e32 v159, v159, v215
	s_waitcnt lgkmcnt(10)
	v_mfma_f32_32x32x16_bf16 v[64:79], v[228:231], v[208:211], v[64:79]
	ds_read_b128 v[228:231], v4 offset:32768
	v_exp_f32_e32 v216, v216
	v_exp_f32_e32 v217, v217
	v_exp_f32_e32 v218, v218
	v_exp_f32_e32 v219, v219
	v_exp_f32_e32 v220, v220
	v_mfma_f32_32x32x16_bf16 v[48:63], v[232:235], v[208:211], v[48:63]
	ds_read_b128 v[232:235], v4 offset:40960
	v_exp_f32_e32 v221, v221
	v_exp_f32_e32 v222, v222
	v_exp_f32_e32 v223, v223
	v_add_f32_e32 v159, v159, v216
	v_add_f32_e32 v159, v159, v217
	s_waitcnt lgkmcnt(10)
	v_mfma_f32_32x32x16_bf16 v[32:47], v[236:239], v[208:211], v[32:47]
	ds_read_b128 v[236:239], v5 offset:32768
	v_add_f32_e32 v159, v159, v218
	v_add_f32_e32 v159, v159, v219
	v_cvt_pk_bf16_f32 v216, v216, v217
	v_cvt_pk_bf16_f32 v217, v218, v219
	v_add_f32_e32 v159, v159, v220
	v_mfma_f32_32x32x16_bf16 v[16:31], v[244:247], v[208:211], v[16:31]
	ds_read_b128 v[244:247], v5 offset:40960
	v_add_f32_e32 v159, v159, v221
	v_cvt_pk_bf16_f32 v218, v220, v221
	v_cvt_pk_bf16_f32 v219, v222, v223
	v_add_f32_e32 v159, v159, v222
	v_add_f32_e32 v159, v159, v223
	s_waitcnt lgkmcnt(10)
	v_mfma_f32_32x32x16_bf16 v[64:79], v[248:251], v[216:219], v[64:79]
	ds_read_b128 v[248:251], v2 offset:49152
	s_add_i32 s26, s26, 1
	s_add_u32 s6, s6, 0x8000
	v_mfma_f32_32x32x16_bf16 v[48:63], v[252:255], v[216:219], v[48:63]
	ds_read_b128 v[252:255], v2 offset:57344
	s_addc_u32 s7, s7, 0
	s_addk_i32 s8, 0x80
	s_waitcnt lgkmcnt(10)
	v_mfma_f32_32x32x16_bf16 v[32:47], v[148:151], v[216:219], v[32:47]
	ds_read_b128 v[148:151], v3 offset:49152
	v_add_u32_e32 v158, 0xffffff80, v158
	v_mfma_f32_32x32x16_bf16 v[16:31], v[152:155], v[216:219], v[16:31]
	ds_read_b128 v[152:155], v3 offset:57344
	s_cmp_lt_i32 s26, s5
	s_cbranch_scc1 .Lfa_top_1

.Lfa_band:
	v_add_u32_e32 v0, s20, v156
	v_add_u32_e32 v2, v0, v148
	v_add_u32_e32 v3, v0, v150
	v_add_u32_e32 v4, v0, v152
	v_add_u32_e32 v5, v0, v154
	v_add_u32_e32 v0, s20, v157
	v_add_u32_e32 v0, 0x10000, v0
	v_add_u32_e32 v6, v0, v149
	v_add_u32_e32 v7, v0, v151
	v_add_u32_e32 v8, v0, v153
	v_add_u32_e32 v9, v0, v155
	v_subrev_u32_e32 v10, s86, v144
	v_subrev_u32_e32 v11, s76, v146
	s_waitcnt vmcnt(0) lgkmcnt(0)
	s_barrier
	ds_read_b128 v[160:163], v2 offset:32768
	ds_read_b128 v[164:167], v2 offset:40960
	ds_read_b128 v[168:171], v3 offset:32768
	ds_read_b128 v[224:227], v3 offset:40960
	ds_read_b128 v[228:231], v4 offset:32768
	ds_read_b128 v[232:235], v4 offset:40960
	ds_read_b128 v[236:239], v5 offset:32768
	ds_read_b128 v[244:247], v5 offset:40960
	ds_read_b128 v[248:251], v2 offset:49152
	ds_read_b128 v[252:255], v2 offset:57344
	ds_read_b128 v[148:151], v3 offset:49152
	ds_read_b128 v[152:155], v3 offset:57344
	s_branch .Lfa_top_b1
.Lfa_band2:
	s_and_b32 s16, s6, 0x8000
	s_cbranch_scc0 .Lfa_top_b0
.Lfa_top_b1:
	s_barrier
	s_mov_b32 s80, 0
	v_lshlrev_b32_e32 v12, 2, v158
	v_sub_u32_e32 v12, 0x20a20, v12
	s_waitcnt lgkmcnt(10)
	v_mfma_f32_32x32x16_bf16 v[96:111], v[160:163], v[128:131], v[80:95]
	ds_read_b128 v[160:163], v4 offset:49152
	s_cmp_ge_u32 s26, s23
	s_cbranch_scc1 .Lfa_nd0_b1
	s_sub_i32 s16, s8, 64
	s_mov_b32 s17, 0
	s_lshl_b64 s[16:17], s[16:17], 11
	s_add_u32 s16, s16, s86
	s_addc_u32 s17, s17, s87
	s_add_u32 s18, s76, s6
	s_addc_u32 s19, s77, s7
	s_add_u32 s18, s18, 0x6d08000
	s_addc_u32 s19, s19, 0
	s_add_i32 m0, s24, 0x0
	s_nop 0
	global_load_lds_dwordx4 v10, s[16:17]
.Lfa_nd0_b1:
	v_mfma_f32_32x32x16_bf16 v[112:127], v[164:167], v[128:131], v[80:95]
	ds_read_b128 v[164:167], v4 offset:57344
	s_cmp_ge_u32 s26, s23
	s_cbranch_scc1 .Lfa_nd1_b1
	s_add_i32 m0, s24, 0x2000
	s_add_u32 s16, s16, 0x10000
	s_addc_u32 s17, s17, 0
	global_load_lds_dwordx4 v10, s[16:17]
.Lfa_nd1_b1:
	s_waitcnt lgkmcnt(10)
	v_mfma_f32_32x32x16_bf16 v[96:111], v[168:171], v[132:135], v[96:111]
	ds_read_b128 v[168:171], v5 offset:49152
	s_cmp_ge_u32 s26, s23
	s_cbranch_scc1 .Lfa_nd2_b1
	s_add_i32 m0, s24, 0x10000
	s_nop 0
	global_load_lds_dwordx4 v11, s[18:19]
.Lfa_nd2_b1:
	v_mfma_f32_32x32x16_bf16 v[112:127], v[224:227], v[132:135], v[112:127]
	ds_read_b128 v[224:227], v5 offset:57344
	s_cmp_ge_u32 s26, s23
	s_cbranch_scc1 .Lfa_nd3_b1
	s_add_i32 m0, s24, 0x12000
	s_add_u32 s18, s18, 0x2000
	s_addc_u32 s19, s19, 0
	global_load_lds_dwordx4 v11, s[18:19]
.Lfa_nd3_b1:
	s_waitcnt lgkmcnt(10)
	v_mfma_f32_32x32x16_bf16 v[96:111], v[228:231], v[136:139], v[96:111]
	ds_read_b128 v[228:231], v6 offset:32768
	s_cmp_ge_u32 s26, s23
	s_cbranch_scc1 .Lfa_nd4_b1
	s_add_i32 m0, s24, 0x4000
	s_add_u32 s16, s16, 0x10000
	s_addc_u32 s17, s17, 0
	global_load_lds_dwordx4 v10, s[16:17]
.Lfa_nd4_b1:
	v_mfma_f32_32x32x16_bf16 v[112:127], v[232:235], v[136:139], v[112:127]
	ds_read_b128 v[232:235], v6 offset:36864
	s_cmp_ge_u32 s26, s23
	s_cbranch_scc1 .Lfa_nd5_b1
	s_add_i32 m0, s24, 0x6000
	s_add_u32 s16, s16, 0x10000
	s_addc_u32 s17, s17, 0
	global_load_lds_dwordx4 v10, s[16:17]
.Lfa_nd5_b1:
	s_waitcnt lgkmcnt(10)
	v_mfma_f32_32x32x16_bf16 v[96:111], v[236:239], v[140:143], v[96:111]
	ds_read_b128 v[236:239], v6 offset:40960
	s_cmp_ge_u32 s26, s23
	s_cbranch_scc1 .Lfa_nd6_b1
	s_add_i32 m0, s24, 0x14000
	s_add_u32 s18, s18, 0x2000
	s_addc_u32 s19, s19, 0
	global_load_lds_dwordx4 v11, s[18:19]
.Lfa_nd6_b1:
	v_mfma_f32_32x32x16_bf16 v[112:127], v[244:247], v[140:143], v[112:127]
	ds_read_b128 v[244:247], v6 offset:45056
	s_cmp_ge_u32 s26, s23
	s_cbranch_scc1 .Lfa_nd7_b1
	s_add_i32 m0, s24, 0x16000
	s_add_u32 s18, s18, 0x2000
	s_addc_u32 s19, s19, 0
	global_load_lds_dwordx4 v11, s[18:19]

.Lfa_retA_b1:
	s_waitcnt lgkmcnt(10)
	v_mfma_f32_32x32x16_bf16 v[192:207], v[248:251], v[128:131], v[80:95]
	ds_read_b128 v[248:251], v7 offset:32768
	v_exp_f32_e32 v96, v96
	v_exp_f32_e32 v97, v97
	v_exp_f32_e32 v98, v98
	v_exp_f32_e32 v99, v99
	v_exp_f32_e32 v100, v100
	v_mfma_f32_32x32x16_bf16 v[208:223], v[252:255], v[128:131], v[80:95]
	ds_read_b128 v[252:255], v7 offset:36864
	v_exp_f32_e32 v101, v101
	v_exp_f32_e32 v102, v102
	v_exp_f32_e32 v103, v103
	v_add_f32_e32 v159, v159, v96
	v_add_f32_e32 v159, v159, v97
	s_waitcnt lgkmcnt(10)
	v_mfma_f32_32x32x16_bf16 v[192:207], v[148:151], v[132:135], v[192:207]
	ds_read_b128 v[148:151], v7 offset:40960
	v_add_f32_e32 v159, v159, v98
	v_add_f32_e32 v159, v159, v99
	v_cvt_pk_bf16_f32 v96, v96, v97
	v_cvt_pk_bf16_f32 v97, v98, v99
	v_add_f32_e32 v159, v159, v100
	v_mfma_f32_32x32x16_bf16 v[208:223], v[152:155], v[132:135], v[208:223]
	ds_read_b128 v[152:155], v7 offset:45056
	v_add_f32_e32 v159, v159, v101
	v_cvt_pk_bf16_f32 v98, v100, v101
	v_cvt_pk_bf16_f32 v99, v102, v103
	v_add_f32_e32 v159, v159, v102
	v_add_f32_e32 v159, v159, v103
	s_waitcnt lgkmcnt(10)
	v_mfma_f32_32x32x16_bf16 v[192:207], v[160:163], v[136:139], v[192:207]
	ds_read_b128 v[160:163], v8 offset:32768
	v_exp_f32_e32 v104, v104
	v_exp_f32_e32 v105, v105
	v_exp_f32_e32 v106, v106
	v_exp_f32_e32 v107, v107
	v_exp_f32_e32 v108, v108
	v_mfma_f32_32x32x16_bf16 v[208:223], v[164:167], v[136:139], v[208:223]
	ds_read_b128 v[164:167], v8 offset:36864
	v_exp_f32_e32 v109, v109
	v_exp_f32_e32 v110, v110
	v_exp_f32_e32 v111, v111
	v_add_f32_e32 v159, v159, v104
	v_add_f32_e32 v159, v159, v105
	s_waitcnt lgkmcnt(10)
	v_mfma_f32_32x32x16_bf16 v[192:207], v[168:171], v[140:143], v[192:207]
	ds_read_b128 v[168:171], v8 offset:40960
	v_add_f32_e32 v159, v159, v106
	v_add_f32_e32 v159, v159, v107
	v_cvt_pk_bf16_f32 v104, v104, v105
	v_cvt_pk_bf16_f32 v105, v106, v107
	v_add_f32_e32 v159, v159, v108
	v_mfma_f32_32x32x16_bf16 v[208:223], v[224:227], v[140:143], v[208:223]
	ds_read_b128 v[224:227], v8 offset:45056
	v_add_f32_e32 v159, v159, v109
	v_cvt_pk_bf16_f32 v106, v108, v109
	v_cvt_pk_bf16_f32 v107, v110, v111
	v_add_f32_e32 v159, v159, v110
	v_add_f32_e32 v159, v159, v111
	s_waitcnt lgkmcnt(10)
	v_mfma_f32_32x32x16_bf16 v[64:79], v[228:231], v[96:99], v[64:79]
	ds_read_b128 v[228:231], v9 offset:32768
	v_exp_f32_e32 v112, v112
	v_exp_f32_e32 v113, v113
	v_exp_f32_e32 v114, v114
	v_exp_f32_e32 v115, v115
	v_exp_f32_e32 v116, v116
	v_mfma_f32_32x32x16_bf16 v[48:63], v[232:235], v[96:99], v[48:63]
	ds_read_b128 v[232:235], v9 offset:36864
	v_exp_f32_e32 v117, v117
	v_exp_f32_e32 v118, v118
	v_exp_f32_e32 v119, v119
	v_add_f32_e32 v159, v159, v112
	v_add_f32_e32 v159, v159, v113
	s_waitcnt lgkmcnt(10)
	v_mfma_f32_32x32x16_bf16 v[32:47], v[236:239], v[96:99], v[32:47]
	ds_read_b128 v[236:239], v9 offset:40960
	v_add_f32_e32 v159, v159, v114
	v_add_f32_e32 v159, v159, v115
	v_cvt_pk_bf16_f32 v112, v112, v113
	v_cvt_pk_bf16_f32 v113, v114, v115
	v_add_f32_e32 v159, v159, v116
	v_mfma_f32_32x32x16_bf16 v[16:31], v[244:247], v[96:99], v[16:31]
	ds_read_b128 v[244:247], v9 offset:45056
	v_add_f32_e32 v159, v159, v117
	v_cvt_pk_bf16_f32 v114, v116, v117
	v_cvt_pk_bf16_f32 v115, v118, v119
	v_add_f32_e32 v159, v159, v118
	v_add_f32_e32 v159, v159, v119
	s_waitcnt lgkmcnt(10)
	v_mfma_f32_32x32x16_bf16 v[64:79], v[248:251], v[104:107], v[64:79]
	ds_read_b128 v[248:251], v6 offset:49152
	v_exp_f32_e32 v120, v120
	v_exp_f32_e32 v121, v121
	v_exp_f32_e32 v122, v122
	v_exp_f32_e32 v123, v123
	v_exp_f32_e32 v124, v124
	v_mfma_f32_32x32x16_bf16 v[48:63], v[252:255], v[104:107], v[48:63]
	ds_read_b128 v[252:255], v6 offset:53248
	v_exp_f32_e32 v125, v125
	v_exp_f32_e32 v126, v126
	v_exp_f32_e32 v127, v127
	v_add_f32_e32 v159, v159, v120
	v_add_f32_e32 v159, v159, v121
	s_waitcnt lgkmcnt(10)
	v_mfma_f32_32x32x16_bf16 v[32:47], v[148:151], v[104:107], v[32:47]
	ds_read_b128 v[148:151], v6 offset:57344
	v_add_f32_e32 v159, v159, v122
	v_add_f32_e32 v159, v159, v123
	v_cvt_pk_bf16_f32 v120, v120, v121
	v_cvt_pk_bf16_f32 v121, v122, v123
	v_add_f32_e32 v159, v159, v124
	v_mfma_f32_32x32x16_bf16 v[16:31], v[152:155], v[104:107], v[16:31]
	ds_read_b128 v[152:155], v6 offset:61440
	v_add_f32_e32 v159, v159, v125
	v_cvt_pk_bf16_f32 v122, v124, v125
	v_cvt_pk_bf16_f32 v123, v126, v127
	v_add_f32_e32 v159, v159, v126
	v_add_f32_e32 v159, v159, v127
	ds_read_b32 v100, v12 offset:256
	ds_read_b32 v101, v12 offset:260
	ds_read_b32 v102, v12 offset:264
	ds_read_b32 v103, v12 offset:268
	ds_read_b32 v108, v12 offset:272
	ds_read_b32 v109, v12 offset:276
	ds_read_b32 v110, v12 offset:280
	ds_read_b32 v111, v12 offset:284
	ds_read_b32 v116, v12 offset:320
	ds_read_b32 v117, v12 offset:324
	ds_read_b32 v118, v12 offset:328
	ds_read_b32 v119, v12 offset:332
	ds_read_b32 v124, v12 offset:336
	ds_read_b32 v125, v12 offset:340
	ds_read_b32 v126, v12 offset:344
	ds_read_b32 v127, v12 offset:348
	s_waitcnt lgkmcnt(0)
	v_add_f32_e32 v192, v192, v100
	v_add_f32_e32 v193, v193, v101
	v_add_f32_e32 v194, v194, v102
	v_add_f32_e32 v195, v195, v103
	v_add_f32_e32 v196, v196, v108
	v_add_f32_e32 v197, v197, v109
	v_add_f32_e32 v198, v198, v110
	v_add_f32_e32 v199, v199, v111
	v_add_f32_e32 v200, v200, v116
	v_add_f32_e32 v201, v201, v117
	v_add_f32_e32 v202, v202, v118
	v_add_f32_e32 v203, v203, v119
	v_add_f32_e32 v204, v204, v124
	v_add_f32_e32 v205, v205, v125
	v_add_f32_e32 v206, v206, v126
	v_add_f32_e32 v207, v207, v127
	ds_read_b32 v100, v12 offset:384
	ds_read_b32 v101, v12 offset:388
	ds_read_b32 v102, v12 offset:392
	ds_read_b32 v103, v12 offset:396
	ds_read_b32 v108, v12 offset:400
	ds_read_b32 v109, v12 offset:404
	ds_read_b32 v110, v12 offset:408
	ds_read_b32 v111, v12 offset:412
	ds_read_b32 v116, v12 offset:448
	ds_read_b32 v117, v12 offset:452
	ds_read_b32 v118, v12 offset:456
	ds_read_b32 v119, v12 offset:460
	ds_read_b32 v124, v12 offset:464
	ds_read_b32 v125, v12 offset:468
	ds_read_b32 v126, v12 offset:472
	ds_read_b32 v127, v12 offset:476
	s_waitcnt lgkmcnt(0)
	v_add_f32_e32 v208, v208, v100
	v_add_f32_e32 v209, v209, v101
	v_add_f32_e32 v210, v210, v102
	v_add_f32_e32 v211, v211, v103
	v_add_f32_e32 v212, v212, v108
	v_add_f32_e32 v213, v213, v109
	v_add_f32_e32 v214, v214, v110
	v_add_f32_e32 v215, v215, v111
	v_add_f32_e32 v216, v216, v116
	v_add_f32_e32 v217, v217, v117
	v_add_f32_e32 v218, v218, v118
	v_add_f32_e32 v219, v219, v119
	v_add_f32_e32 v220, v220, v124
	v_add_f32_e32 v221, v221, v125
	v_add_f32_e32 v222, v222, v126
	v_add_f32_e32 v223, v223, v127
	v_max3_f32 v190, v192, v193, v194
	v_max3_f32 v190, v190, v195, v196
	v_max3_f32 v190, v190, v197, v198
	v_max3_f32 v190, v190, v199, v200
	v_max3_f32 v190, v190, v201, v202
	v_max3_f32 v190, v190, v203, v204
	v_max3_f32 v190, v190, v205, v206
	v_max3_f32 v190, v190, v207, v207
	v_max3_f32 v191, v208, v209, v210
	v_max3_f32 v191, v191, v211, v212
	v_max3_f32 v191, v191, v213, v214
	v_max3_f32 v191, v191, v215, v216
	v_max3_f32 v191, v191, v217, v218
	v_max3_f32 v191, v191, v219, v220
	v_max3_f32 v191, v191, v221, v222
	v_max3_f32 v191, v191, v223, v223
	v_max_f32_e32 v0, v190, v191
	s_nop 0
	v_cmp_lt_f32_e32 vcc, s67, v0
	s_or_b64 vcc, vcc, s[18:19]
	s_cbranch_vccnz .Lfa_rareB_b1
.Lfa_retB_b1:
	s_waitcnt lgkmcnt(10)
	v_mfma_f32_32x32x16_bf16 v[64:79], v[160:163], v[112:115], v[64:79]
	ds_read_b128 v[160:163], v7 offset:49152
	v_exp_f32_e32 v192, v192
	v_exp_f32_e32 v193, v193
	v_exp_f32_e32 v194, v194
	v_exp_f32_e32 v195, v195
	v_exp_f32_e32 v196, v196
	v_mfma_f32_32x32x16_bf16 v[48:63], v[164:167], v[112:115], v[48:63]
	ds_read_b128 v[164:167], v7 offset:53248
	v_exp_f32_e32 v197, v197
	v_exp_f32_e32 v198, v198
	v_exp_f32_e32 v199, v199
	v_add_f32_e32 v159, v159, v192
	v_add_f32_e32 v159, v159, v193
	s_waitcnt lgkmcnt(10)
	v_mfma_f32_32x32x16_bf16 v[32:47], v[168:171], v[112:115], v[32:47]
	ds_read_b128 v[168:171], v7 offset:57344
	v_add_f32_e32 v159, v159, v194
	v_add_f32_e32 v159, v159, v195
	v_cvt_pk_bf16_f32 v192, v192, v193
	v_cvt_pk_bf16_f32 v193, v194, v195
	v_add_f32_e32 v159, v159, v196
	v_mfma_f32_32x32x16_bf16 v[16:31], v[224:227], v[112:115], v[16:31]
	ds_read_b128 v[224:227], v7 offset:61440
	v_add_f32_e32 v159, v159, v197
	v_cvt_pk_bf16_f32 v194, v196, v197
	v_cvt_pk_bf16_f32 v195, v198, v199
	v_add_f32_e32 v159, v159, v198
	v_add_f32_e32 v159, v159, v199
	s_waitcnt lgkmcnt(10)
	v_mfma_f32_32x32x16_bf16 v[64:79], v[228:231], v[120:123], v[64:79]
	ds_read_b128 v[228:231], v8 offset:49152
	v_mfma_f32_32x32x16_bf16 v[48:63], v[232:235], v[120:123], v[48:63]
	ds_read_b128 v[232:235], v8 offset:53248
	s_waitcnt lgkmcnt(10)
	v_mfma_f32_32x32x16_bf16 v[32:47], v[236:239], v[120:123], v[32:47]
	ds_read_b128 v[236:239], v8 offset:57344
	v_mfma_f32_32x32x16_bf16 v[16:31], v[244:247], v[120:123], v[16:31]
	ds_read_b128 v[244:247], v8 offset:61440
	s_cmp_lg_u32 s80, 0
	s_cbranch_scc1 .Lfa_fixO_b1
.Lfa_retO_b1:
	s_waitcnt lgkmcnt(10)
	v_mfma_f32_32x32x16_bf16 v[64:79], v[248:251], v[192:195], v[64:79]
	ds_read_b128 v[248:251], v9 offset:49152
	v_exp_f32_e32 v200, v200
	v_exp_f32_e32 v201, v201
	v_exp_f32_e32 v202, v202
	v_exp_f32_e32 v203, v203
	v_exp_f32_e32 v204, v204
	v_mfma_f32_32x32x16_bf16 v[48:63], v[252:255], v[192:195], v[48:63]
	ds_read_b128 v[252:255], v9 offset:53248
	v_exp_f32_e32 v205, v205
	v_exp_f32_e32 v206, v206
	v_exp_f32_e32 v207, v207
	v_add_f32_e32 v159, v159, v200
	v_add_f32_e32 v159, v159, v201
	s_waitcnt lgkmcnt(10)
	v_mfma_f32_32x32x16_bf16 v[32:47], v[148:151], v[192:195], v[32:47]
	ds_read_b128 v[148:151], v9 offset:57344
	v_add_f32_e32 v159, v159, v202
	v_add_f32_e32 v159, v159, v203
	v_cvt_pk_bf16_f32 v200, v200, v201
	v_cvt_pk_bf16_f32 v201, v202, v203
	v_add_f32_e32 v159, v159, v204
	v_mfma_f32_32x32x16_bf16 v[16:31], v[152:155], v[192:195], v[16:31]
	ds_read_b128 v[152:155], v9 offset:61440
	v_add_f32_e32 v159, v159, v205
	v_cvt_pk_bf16_f32 v202, v204, v205
	v_cvt_pk_bf16_f32 v203, v206, v207
	v_add_f32_e32 v159, v159, v206
	v_add_f32_e32 v159, v159, v207
	s_waitcnt vmcnt(0)
	s_barrier
	s_waitcnt lgkmcnt(10)
	v_mfma_f32_32x32x16_bf16 v[64:79], v[160:163], v[200:203], v[64:79]
	ds_read_b128 v[160:163], v2
	v_exp_f32_e32 v208, v208
	v_exp_f32_e32 v209, v209
	v_exp_f32_e32 v210, v210
	v_exp_f32_e32 v211, v211
	v_exp_f32_e32 v212, v212
	v_mfma_f32_32x32x16_bf16 v[48:63], v[164:167], v[200:203], v[48:63]
	ds_read_b128 v[164:167], v2 offset:8192
	v_exp_f32_e32 v213, v213
	v_exp_f32_e32 v214, v214
	v_exp_f32_e32 v215, v215
	v_add_f32_e32 v159, v159, v208
	v_add_f32_e32 v159, v159, v209
	s_waitcnt lgkmcnt(10)
	v_mfma_f32_32x32x16_bf16 v[32:47], v[168:171], v[200:203], v[32:47]
	ds_read_b128 v[168:171], v3
	v_add_f32_e32 v159, v159, v210
	v_add_f32_e32 v159, v159, v211
	v_cvt_pk_bf16_f32 v208, v208, v209
	v_cvt_pk_bf16_f32 v209, v210, v211
	v_add_f32_e32 v159, v159, v212
	v_mfma_f32_32x32x16_bf16 v[16:31], v[224:227], v[200:203], v[16:31]
	ds_read_b128 v[224:227], v3 offset:8192
	v_add_f32_e32 v159, v159, v213
	v_cvt_pk_bf16_f32 v210, v212, v213
	v_cvt_pk_bf16_f32 v211, v214, v215
	v_add_f32_e32 v159, v159, v214
	v_add_f32_e32 v159, v159, v215
	s_waitcnt lgkmcnt(10)
	v_mfma_f32_32x32x16_bf16 v[64:79], v[228:231], v[208:211], v[64:79]
	ds_read_b128 v[228:231], v4
	v_exp_f32_e32 v216, v216
	v_exp_f32_e32 v217, v217
	v_exp_f32_e32 v218, v218
	v_exp_f32_e32 v219, v219
	v_exp_f32_e32 v220, v220
	v_mfma_f32_32x32x16_bf16 v[48:63], v[232:235], v[208:211], v[48:63]
	ds_read_b128 v[232:235], v4 offset:8192
	v_exp_f32_e32 v221, v221
	v_exp_f32_e32 v222, v222
	v_exp_f32_e32 v223, v223
	v_add_f32_e32 v159, v159, v216
	v_add_f32_e32 v159, v159, v217
	s_waitcnt lgkmcnt(10)
	v_mfma_f32_32x32x16_bf16 v[32:47], v[236:239], v[208:211], v[32:47]
	ds_read_b128 v[236:239], v5
	v_add_f32_e32 v159, v159, v218
	v_add_f32_e32 v159, v159, v219
	v_cvt_pk_bf16_f32 v216, v216, v217
	v_cvt_pk_bf16_f32 v217, v218, v219
	v_add_f32_e32 v159, v159, v220
	v_mfma_f32_32x32x16_bf16 v[16:31], v[244:247], v[208:211], v[16:31]
	ds_read_b128 v[244:247], v5 offset:8192
	v_add_f32_e32 v159, v159, v221
	v_cvt_pk_bf16_f32 v218, v220, v221
	v_cvt_pk_bf16_f32 v219, v222, v223
	v_add_f32_e32 v159, v159, v222
	v_add_f32_e32 v159, v159, v223
	s_waitcnt lgkmcnt(10)
	v_mfma_f32_32x32x16_bf16 v[64:79], v[248:251], v[216:219], v[64:79]
	ds_read_b128 v[248:251], v2 offset:16384
	s_add_i32 s26, s26, 1
	s_add_u32 s6, s6, 0x8000
	v_mfma_f32_32x32x16_bf16 v[48:63], v[252:255], v[216:219], v[48:63]
	ds_read_b128 v[252:255], v2 offset:24576
	s_addc_u32 s7, s7, 0
	s_addk_i32 s8, 0x80
	s_waitcnt lgkmcnt(10)
	v_mfma_f32_32x32x16_bf16 v[32:47], v[148:151], v[216:219], v[32:47]
	ds_read_b128 v[148:151], v3 offset:16384
	v_add_u32_e32 v158, 0xffffff80, v158
	v_mfma_f32_32x32x16_bf16 v[16:31], v[152:155], v[216:219], v[16:31]
	ds_read_b128 v[152:155], v3 offset:24576
	s_cmp_eq_u32 s25, s26
	s_cbranch_scc1 .Lfa_bexit
.Lfa_top_b0:
	s_barrier
	s_mov_b32 s80, 0
	v_lshlrev_b32_e32 v12, 2, v158
	v_sub_u32_e32 v12, 0x20a20, v12
	s_waitcnt lgkmcnt(10)
	v_mfma_f32_32x32x16_bf16 v[96:111], v[160:163], v[128:131], v[80:95]
	ds_read_b128 v[160:163], v4 offset:16384
	s_cmp_ge_u32 s26, s23
	s_cbranch_scc1 .Lfa_nd0_b0
	s_sub_i32 s16, s8, 64
	s_mov_b32 s17, 0
	s_lshl_b64 s[16:17], s[16:17], 11
	s_add_u32 s16, s16, s86
	s_addc_u32 s17, s17, s87
	s_add_u32 s18, s76, s6
	s_addc_u32 s19, s77, s7
	s_add_u32 s18, s18, 0x6d08000
	s_addc_u32 s19, s19, 0
	s_add_i32 m0, s24, 0x8000
	s_nop 0
	global_load_lds_dwordx4 v10, s[16:17]
.Lfa_nd0_b0:
	v_mfma_f32_32x32x16_bf16 v[112:127], v[164:167], v[128:131], v[80:95]
	ds_read_b128 v[164:167], v4 offset:24576
	s_cmp_ge_u32 s26, s23
	s_cbranch_scc1 .Lfa_nd1_b0
	s_add_i32 m0, s24, 0xa000
	s_add_u32 s16, s16, 0x10000
	s_addc_u32 s17, s17, 0
	global_load_lds_dwordx4 v10, s[16:17]
.Lfa_nd1_b0:
	s_waitcnt lgkmcnt(10)
	v_mfma_f32_32x32x16_bf16 v[96:111], v[168:171], v[132:135], v[96:111]
	ds_read_b128 v[168:171], v5 offset:16384
	s_cmp_ge_u32 s26, s23
	s_cbranch_scc1 .Lfa_nd2_b0
	s_add_i32 m0, s24, 0x18000
	s_nop 0
	global_load_lds_dwordx4 v11, s[18:19]
.Lfa_nd2_b0:
	v_mfma_f32_32x32x16_bf16 v[112:127], v[224:227], v[132:135], v[112:127]
	ds_read_b128 v[224:227], v5 offset:24576
	s_cmp_ge_u32 s26, s23
	s_cbranch_scc1 .Lfa_nd3_b0
	s_add_i32 m0, s24, 0x1a000
	s_add_u32 s18, s18, 0x2000
	s_addc_u32 s19, s19, 0
	global_load_lds_dwordx4 v11, s[18:19]
.Lfa_nd3_b0:
	s_waitcnt lgkmcnt(10)
	v_mfma_f32_32x32x16_bf16 v[96:111], v[228:231], v[136:139], v[96:111]
	ds_read_b128 v[228:231], v6
	s_cmp_ge_u32 s26, s23
	s_cbranch_scc1 .Lfa_nd4_b0
	s_add_i32 m0, s24, 0xc000
	s_add_u32 s16, s16, 0x10000
	s_addc_u32 s17, s17, 0
	global_load_lds_dwordx4 v10, s[16:17]
.Lfa_nd4_b0:
	v_mfma_f32_32x32x16_bf16 v[112:127], v[232:235], v[136:139], v[112:127]
	ds_read_b128 v[232:235], v6 offset:4096
	s_cmp_ge_u32 s26, s23
	s_cbranch_scc1 .Lfa_nd5_b0
	s_add_i32 m0, s24, 0xe000
	s_add_u32 s16, s16, 0x10000
	s_addc_u32 s17, s17, 0
	global_load_lds_dwordx4 v10, s[16:17]
.Lfa_nd5_b0:
	s_waitcnt lgkmcnt(10)
	v_mfma_f32_32x32x16_bf16 v[96:111], v[236:239], v[140:143], v[96:111]
	ds_read_b128 v[236:239], v6 offset:8192
	s_cmp_ge_u32 s26, s23
	s_cbranch_scc1 .Lfa_nd6_b0
	s_add_i32 m0, s24, 0x1c000
	s_add_u32 s18, s18, 0x2000
	s_addc_u32 s19, s19, 0
	global_load_lds_dwordx4 v11, s[18:19]
.Lfa_nd6_b0:
	v_mfma_f32_32x32x16_bf16 v[112:127], v[244:247], v[140:143], v[112:127]
	ds_read_b128 v[244:247], v6 offset:12288
	s_cmp_ge_u32 s26, s23
	s_cbranch_scc1 .Lfa_nd7_b0
	s_add_i32 m0, s24, 0x1e000
	s_add_u32 s18, s18, 0x2000
	s_addc_u32 s19, s19, 0
	global_load_lds_dwordx4 v11, s[18:19]

.Lfa_retA_b0:
	s_waitcnt lgkmcnt(10)
	v_mfma_f32_32x32x16_bf16 v[192:207], v[248:251], v[128:131], v[80:95]
	ds_read_b128 v[248:251], v7
	v_exp_f32_e32 v96, v96
	v_exp_f32_e32 v97, v97
	v_exp_f32_e32 v98, v98
	v_exp_f32_e32 v99, v99
	v_exp_f32_e32 v100, v100
	v_mfma_f32_32x32x16_bf16 v[208:223], v[252:255], v[128:131], v[80:95]
	ds_read_b128 v[252:255], v7 offset:4096
	v_exp_f32_e32 v101, v101
	v_exp_f32_e32 v102, v102
	v_exp_f32_e32 v103, v103
	v_add_f32_e32 v159, v159, v96
	v_add_f32_e32 v159, v159, v97
	s_waitcnt lgkmcnt(10)
	v_mfma_f32_32x32x16_bf16 v[192:207], v[148:151], v[132:135], v[192:207]
	ds_read_b128 v[148:151], v7 offset:8192
	v_add_f32_e32 v159, v159, v98
	v_add_f32_e32 v159, v159, v99
	v_cvt_pk_bf16_f32 v96, v96, v97
	v_cvt_pk_bf16_f32 v97, v98, v99
	v_add_f32_e32 v159, v159, v100
	v_mfma_f32_32x32x16_bf16 v[208:223], v[152:155], v[132:135], v[208:223]
	ds_read_b128 v[152:155], v7 offset:12288
	v_add_f32_e32 v159, v159, v101
	v_cvt_pk_bf16_f32 v98, v100, v101
	v_cvt_pk_bf16_f32 v99, v102, v103
	v_add_f32_e32 v159, v159, v102
	v_add_f32_e32 v159, v159, v103
	s_waitcnt lgkmcnt(10)
	v_mfma_f32_32x32x16_bf16 v[192:207], v[160:163], v[136:139], v[192:207]
	ds_read_b128 v[160:163], v8
	v_exp_f32_e32 v104, v104
	v_exp_f32_e32 v105, v105
	v_exp_f32_e32 v106, v106
	v_exp_f32_e32 v107, v107
	v_exp_f32_e32 v108, v108
	v_mfma_f32_32x32x16_bf16 v[208:223], v[164:167], v[136:139], v[208:223]
	ds_read_b128 v[164:167], v8 offset:4096
	v_exp_f32_e32 v109, v109
	v_exp_f32_e32 v110, v110
	v_exp_f32_e32 v111, v111
	v_add_f32_e32 v159, v159, v104
	v_add_f32_e32 v159, v159, v105
	s_waitcnt lgkmcnt(10)
	v_mfma_f32_32x32x16_bf16 v[192:207], v[168:171], v[140:143], v[192:207]
	ds_read_b128 v[168:171], v8 offset:8192
	v_add_f32_e32 v159, v159, v106
	v_add_f32_e32 v159, v159, v107
	v_cvt_pk_bf16_f32 v104, v104, v105
	v_cvt_pk_bf16_f32 v105, v106, v107
	v_add_f32_e32 v159, v159, v108
	v_mfma_f32_32x32x16_bf16 v[208:223], v[224:227], v[140:143], v[208:223]
	ds_read_b128 v[224:227], v8 offset:12288
	v_add_f32_e32 v159, v159, v109
	v_cvt_pk_bf16_f32 v106, v108, v109
	v_cvt_pk_bf16_f32 v107, v110, v111
	v_add_f32_e32 v159, v159, v110
	v_add_f32_e32 v159, v159, v111
	s_waitcnt lgkmcnt(10)
	v_mfma_f32_32x32x16_bf16 v[64:79], v[228:231], v[96:99], v[64:79]
	ds_read_b128 v[228:231], v9
	v_exp_f32_e32 v112, v112
	v_exp_f32_e32 v113, v113
	v_exp_f32_e32 v114, v114
	v_exp_f32_e32 v115, v115
	v_exp_f32_e32 v116, v116
	v_mfma_f32_32x32x16_bf16 v[48:63], v[232:235], v[96:99], v[48:63]
	ds_read_b128 v[232:235], v9 offset:4096
	v_exp_f32_e32 v117, v117
	v_exp_f32_e32 v118, v118
	v_exp_f32_e32 v119, v119
	v_add_f32_e32 v159, v159, v112
	v_add_f32_e32 v159, v159, v113
	s_waitcnt lgkmcnt(10)
	v_mfma_f32_32x32x16_bf16 v[32:47], v[236:239], v[96:99], v[32:47]
	ds_read_b128 v[236:239], v9 offset:8192
	v_add_f32_e32 v159, v159, v114
	v_add_f32_e32 v159, v159, v115
	v_cvt_pk_bf16_f32 v112, v112, v113
	v_cvt_pk_bf16_f32 v113, v114, v115
	v_add_f32_e32 v159, v159, v116
	v_mfma_f32_32x32x16_bf16 v[16:31], v[244:247], v[96:99], v[16:31]
	ds_read_b128 v[244:247], v9 offset:12288
	v_add_f32_e32 v159, v159, v117
	v_cvt_pk_bf16_f32 v114, v116, v117
	v_cvt_pk_bf16_f32 v115, v118, v119
	v_add_f32_e32 v159, v159, v118
	v_add_f32_e32 v159, v159, v119
	s_waitcnt lgkmcnt(10)
	v_mfma_f32_32x32x16_bf16 v[64:79], v[248:251], v[104:107], v[64:79]
	ds_read_b128 v[248:251], v6 offset:16384
	v_exp_f32_e32 v120, v120
	v_exp_f32_e32 v121, v121
	v_exp_f32_e32 v122, v122
	v_exp_f32_e32 v123, v123
	v_exp_f32_e32 v124, v124
	v_mfma_f32_32x32x16_bf16 v[48:63], v[252:255], v[104:107], v[48:63]
	ds_read_b128 v[252:255], v6 offset:20480
	v_exp_f32_e32 v125, v125
	v_exp_f32_e32 v126, v126
	v_exp_f32_e32 v127, v127
	v_add_f32_e32 v159, v159, v120
	v_add_f32_e32 v159, v159, v121
	s_waitcnt lgkmcnt(10)
	v_mfma_f32_32x32x16_bf16 v[32:47], v[148:151], v[104:107], v[32:47]
	ds_read_b128 v[148:151], v6 offset:24576
	v_add_f32_e32 v159, v159, v122
	v_add_f32_e32 v159, v159, v123
	v_cvt_pk_bf16_f32 v120, v120, v121
	v_cvt_pk_bf16_f32 v121, v122, v123
	v_add_f32_e32 v159, v159, v124
	v_mfma_f32_32x32x16_bf16 v[16:31], v[152:155], v[104:107], v[16:31]
	ds_read_b128 v[152:155], v6 offset:28672
	v_add_f32_e32 v159, v159, v125
	v_cvt_pk_bf16_f32 v122, v124, v125
	v_cvt_pk_bf16_f32 v123, v126, v127
	v_add_f32_e32 v159, v159, v126
	v_add_f32_e32 v159, v159, v127
	ds_read_b32 v100, v12 offset:256
	ds_read_b32 v101, v12 offset:260
	ds_read_b32 v102, v12 offset:264
	ds_read_b32 v103, v12 offset:268
	ds_read_b32 v108, v12 offset:272
	ds_read_b32 v109, v12 offset:276
	ds_read_b32 v110, v12 offset:280
	ds_read_b32 v111, v12 offset:284
	ds_read_b32 v116, v12 offset:320
	ds_read_b32 v117, v12 offset:324
	ds_read_b32 v118, v12 offset:328
	ds_read_b32 v119, v12 offset:332
	ds_read_b32 v124, v12 offset:336
	ds_read_b32 v125, v12 offset:340
	ds_read_b32 v126, v12 offset:344
	ds_read_b32 v127, v12 offset:348
	s_waitcnt lgkmcnt(0)
	v_add_f32_e32 v192, v192, v100
	v_add_f32_e32 v193, v193, v101
	v_add_f32_e32 v194, v194, v102
	v_add_f32_e32 v195, v195, v103
	v_add_f32_e32 v196, v196, v108
	v_add_f32_e32 v197, v197, v109
	v_add_f32_e32 v198, v198, v110
	v_add_f32_e32 v199, v199, v111
	v_add_f32_e32 v200, v200, v116
	v_add_f32_e32 v201, v201, v117
	v_add_f32_e32 v202, v202, v118
	v_add_f32_e32 v203, v203, v119
	v_add_f32_e32 v204, v204, v124
	v_add_f32_e32 v205, v205, v125
	v_add_f32_e32 v206, v206, v126
	v_add_f32_e32 v207, v207, v127
	ds_read_b32 v100, v12 offset:384
	ds_read_b32 v101, v12 offset:388
	ds_read_b32 v102, v12 offset:392
	ds_read_b32 v103, v12 offset:396
	ds_read_b32 v108, v12 offset:400
	ds_read_b32 v109, v12 offset:404
	ds_read_b32 v110, v12 offset:408
	ds_read_b32 v111, v12 offset:412
	ds_read_b32 v116, v12 offset:448
	ds_read_b32 v117, v12 offset:452
	ds_read_b32 v118, v12 offset:456
	ds_read_b32 v119, v12 offset:460
	ds_read_b32 v124, v12 offset:464
	ds_read_b32 v125, v12 offset:468
	ds_read_b32 v126, v12 offset:472
	ds_read_b32 v127, v12 offset:476
	s_waitcnt lgkmcnt(0)
	v_add_f32_e32 v208, v208, v100
	v_add_f32_e32 v209, v209, v101
	v_add_f32_e32 v210, v210, v102
	v_add_f32_e32 v211, v211, v103
	v_add_f32_e32 v212, v212, v108
	v_add_f32_e32 v213, v213, v109
	v_add_f32_e32 v214, v214, v110
	v_add_f32_e32 v215, v215, v111
	v_add_f32_e32 v216, v216, v116
	v_add_f32_e32 v217, v217, v117
	v_add_f32_e32 v218, v218, v118
	v_add_f32_e32 v219, v219, v119
	v_add_f32_e32 v220, v220, v124
	v_add_f32_e32 v221, v221, v125
	v_add_f32_e32 v222, v222, v126
	v_add_f32_e32 v223, v223, v127
	v_max3_f32 v190, v192, v193, v194
	v_max3_f32 v190, v190, v195, v196
	v_max3_f32 v190, v190, v197, v198
	v_max3_f32 v190, v190, v199, v200
	v_max3_f32 v190, v190, v201, v202
	v_max3_f32 v190, v190, v203, v204
	v_max3_f32 v190, v190, v205, v206
	v_max3_f32 v190, v190, v207, v207
	v_max3_f32 v191, v208, v209, v210
	v_max3_f32 v191, v191, v211, v212
	v_max3_f32 v191, v191, v213, v214
	v_max3_f32 v191, v191, v215, v216
	v_max3_f32 v191, v191, v217, v218
	v_max3_f32 v191, v191, v219, v220
	v_max3_f32 v191, v191, v221, v222
	v_max3_f32 v191, v191, v223, v223
	v_max_f32_e32 v0, v190, v191
	s_nop 0
	v_cmp_lt_f32_e32 vcc, s67, v0
	s_or_b64 vcc, vcc, s[18:19]
	s_cbranch_vccnz .Lfa_rareB_b0
.Lfa_retB_b0:
	s_waitcnt lgkmcnt(10)
	v_mfma_f32_32x32x16_bf16 v[64:79], v[160:163], v[112:115], v[64:79]
	ds_read_b128 v[160:163], v7 offset:16384
	v_exp_f32_e32 v192, v192
	v_exp_f32_e32 v193, v193
	v_exp_f32_e32 v194, v194
	v_exp_f32_e32 v195, v195
	v_exp_f32_e32 v196, v196
	v_mfma_f32_32x32x16_bf16 v[48:63], v[164:167], v[112:115], v[48:63]
	ds_read_b128 v[164:167], v7 offset:20480
	v_exp_f32_e32 v197, v197
	v_exp_f32_e32 v198, v198
	v_exp_f32_e32 v199, v199
	v_add_f32_e32 v159, v159, v192
	v_add_f32_e32 v159, v159, v193
	s_waitcnt lgkmcnt(10)
	v_mfma_f32_32x32x16_bf16 v[32:47], v[168:171], v[112:115], v[32:47]
	ds_read_b128 v[168:171], v7 offset:24576
	v_add_f32_e32 v159, v159, v194
	v_add_f32_e32 v159, v159, v195
	v_cvt_pk_bf16_f32 v192, v192, v193
	v_cvt_pk_bf16_f32 v193, v194, v195
	v_add_f32_e32 v159, v159, v196
	v_mfma_f32_32x32x16_bf16 v[16:31], v[224:227], v[112:115], v[16:31]
	ds_read_b128 v[224:227], v7 offset:28672
	v_add_f32_e32 v159, v159, v197
	v_cvt_pk_bf16_f32 v194, v196, v197
	v_cvt_pk_bf16_f32 v195, v198, v199
	v_add_f32_e32 v159, v159, v198
	v_add_f32_e32 v159, v159, v199
	s_waitcnt lgkmcnt(10)
	v_mfma_f32_32x32x16_bf16 v[64:79], v[228:231], v[120:123], v[64:79]
	ds_read_b128 v[228:231], v8 offset:16384
	v_mfma_f32_32x32x16_bf16 v[48:63], v[232:235], v[120:123], v[48:63]
	ds_read_b128 v[232:235], v8 offset:20480
	s_waitcnt lgkmcnt(10)
	v_mfma_f32_32x32x16_bf16 v[32:47], v[236:239], v[120:123], v[32:47]
	ds_read_b128 v[236:239], v8 offset:24576
	v_mfma_f32_32x32x16_bf16 v[16:31], v[244:247], v[120:123], v[16:31]
	ds_read_b128 v[244:247], v8 offset:28672
	s_cmp_lg_u32 s80, 0
	s_cbranch_scc1 .Lfa_fixO_b0
.Lfa_retO_b0:
	s_waitcnt lgkmcnt(10)
	v_mfma_f32_32x32x16_bf16 v[64:79], v[248:251], v[192:195], v[64:79]
	ds_read_b128 v[248:251], v9 offset:16384
	v_exp_f32_e32 v200, v200
	v_exp_f32_e32 v201, v201
	v_exp_f32_e32 v202, v202
	v_exp_f32_e32 v203, v203
	v_exp_f32_e32 v204, v204
	v_mfma_f32_32x32x16_bf16 v[48:63], v[252:255], v[192:195], v[48:63]
	ds_read_b128 v[252:255], v9 offset:20480
	v_exp_f32_e32 v205, v205
	v_exp_f32_e32 v206, v206
	v_exp_f32_e32 v207, v207
	v_add_f32_e32 v159, v159, v200
	v_add_f32_e32 v159, v159, v201
	s_waitcnt lgkmcnt(10)
	v_mfma_f32_32x32x16_bf16 v[32:47], v[148:151], v[192:195], v[32:47]
	ds_read_b128 v[148:151], v9 offset:24576
	v_add_f32_e32 v159, v159, v202
	v_add_f32_e32 v159, v159, v203
	v_cvt_pk_bf16_f32 v200, v200, v201
	v_cvt_pk_bf16_f32 v201, v202, v203
	v_add_f32_e32 v159, v159, v204
	v_mfma_f32_32x32x16_bf16 v[16:31], v[152:155], v[192:195], v[16:31]
	ds_read_b128 v[152:155], v9 offset:28672
	v_add_f32_e32 v159, v159, v205
	v_cvt_pk_bf16_f32 v202, v204, v205
	v_cvt_pk_bf16_f32 v203, v206, v207
	v_add_f32_e32 v159, v159, v206
	v_add_f32_e32 v159, v159, v207
	s_waitcnt vmcnt(0)
	s_barrier
	s_waitcnt lgkmcnt(10)
	v_mfma_f32_32x32x16_bf16 v[64:79], v[160:163], v[200:203], v[64:79]
	ds_read_b128 v[160:163], v2 offset:32768
	v_exp_f32_e32 v208, v208
	v_exp_f32_e32 v209, v209
	v_exp_f32_e32 v210, v210
	v_exp_f32_e32 v211, v211
	v_exp_f32_e32 v212, v212
	v_mfma_f32_32x32x16_bf16 v[48:63], v[164:167], v[200:203], v[48:63]
	ds_read_b128 v[164:167], v2 offset:40960
	v_exp_f32_e32 v213, v213
	v_exp_f32_e32 v214, v214
	v_exp_f32_e32 v215, v215
	v_add_f32_e32 v159, v159, v208
	v_add_f32_e32 v159, v159, v209
	s_waitcnt lgkmcnt(10)
	v_mfma_f32_32x32x16_bf16 v[32:47], v[168:171], v[200:203], v[32:47]
	ds_read_b128 v[168:171], v3 offset:32768
	v_add_f32_e32 v159, v159, v210
	v_add_f32_e32 v159, v159, v211
	v_cvt_pk_bf16_f32 v208, v208, v209
	v_cvt_pk_bf16_f32 v209, v210, v211
	v_add_f32_e32 v159, v159, v212
	v_mfma_f32_32x32x16_bf16 v[16:31], v[224:227], v[200:203], v[16:31]
	ds_read_b128 v[224:227], v3 offset:40960
	v_add_f32_e32 v159, v159, v213
	v_cvt_pk_bf16_f32 v210, v212, v213
	v_cvt_pk_bf16_f32 v211, v214, v215
	v_add_f32_e32 v159, v159, v214
	v_add_f32_e32 v159, v159, v215
	s_waitcnt lgkmcnt(10)
	v_mfma_f32_32x32x16_bf16 v[64:79], v[228:231], v[208:211], v[64:79]
	ds_read_b128 v[228:231], v4 offset:32768
	v_exp_f32_e32 v216, v216
	v_exp_f32_e32 v217, v217
	v_exp_f32_e32 v218, v218
	v_exp_f32_e32 v219, v219
	v_exp_f32_e32 v220, v220
	v_mfma_f32_32x32x16_bf16 v[48:63], v[232:235], v[208:211], v[48:63]
	ds_read_b128 v[232:235], v4 offset:40960
	v_exp_f32_e32 v221, v221
	v_exp_f32_e32 v222, v222
	v_exp_f32_e32 v223, v223
	v_add_f32_e32 v159, v159, v216
	v_add_f32_e32 v159, v159, v217
	s_waitcnt lgkmcnt(10)
	v_mfma_f32_32x32x16_bf16 v[32:47], v[236:239], v[208:211], v[32:47]
	ds_read_b128 v[236:239], v5 offset:32768
	v_add_f32_e32 v159, v159, v218
	v_add_f32_e32 v159, v159, v219
	v_cvt_pk_bf16_f32 v216, v216, v217
	v_cvt_pk_bf16_f32 v217, v218, v219
	v_add_f32_e32 v159, v159, v220
	v_mfma_f32_32x32x16_bf16 v[16:31], v[244:247], v[208:211], v[16:31]
	ds_read_b128 v[244:247], v5 offset:40960
	v_add_f32_e32 v159, v159, v221
	v_cvt_pk_bf16_f32 v218, v220, v221
	v_cvt_pk_bf16_f32 v219, v222, v223
	v_add_f32_e32 v159, v159, v222
	v_add_f32_e32 v159, v159, v223
	s_waitcnt lgkmcnt(10)
	v_mfma_f32_32x32x16_bf16 v[64:79], v[248:251], v[216:219], v[64:79]
	ds_read_b128 v[248:251], v2 offset:49152
	s_add_i32 s26, s26, 1
	s_add_u32 s6, s6, 0x8000
	v_mfma_f32_32x32x16_bf16 v[48:63], v[252:255], v[216:219], v[48:63]
	ds_read_b128 v[252:255], v2 offset:57344
	s_addc_u32 s7, s7, 0
	s_addk_i32 s8, 0x80
	s_waitcnt lgkmcnt(10)
	v_mfma_f32_32x32x16_bf16 v[32:47], v[148:151], v[216:219], v[32:47]
	ds_read_b128 v[148:151], v3 offset:49152
	v_add_u32_e32 v158, 0xffffff80, v158
	v_mfma_f32_32x32x16_bf16 v[16:31], v[152:155], v[216:219], v[16:31]
	ds_read_b128 v[152:155], v3 offset:57344
	s_cmp_eq_u32 s25, s26
	s_cbranch_scc0 .Lfa_top_b1
